# grid barrier 1 arrival/poll hand-written like barriers 2-5 (its first-use XCD census kept)
# baseline (speedup 1.0000x reference)
; __device__ __forceinline__ unsigned xb_ld(unsigned* p)              { return __hip_atomic_load(p, __ATOMIC_RELAXED, __HIP_MEMORY_SCOPE_AGENT); }
; __device__ __forceinline__ unsigned xb_add(unsigned* p, unsigned v) { return __hip_atomic_fetch_add(p, v, __ATOMIC_RELAXED, __HIP_MEMORY_SCOPE_AGENT); }
; #define XB_SPIN(cond, bar) do { unsigned _sp = 0; while (cond) { __builtin_amdgcn_s_sleep(1); \
;     if ((++_sp & 255u) == 0u) { if (xb_ld(&(bar)[XB_TMO])) break; if (_sp > XB_SPIN_CAP) { atomicAdd(&(bar)[XB_TMO], 1u); break; } } } } while (0)
; __device__ __forceinline__ void xcd_barrier(const XcdBarrier& b) {
;     asm volatile("s_waitcnt vmcnt(0)" ::: "memory");
;     __syncthreads();
;     if (threadIdx.x == 0) {
;         unsigned* bar = b.bar;
;         __builtin_amdgcn_s_waitcnt(0);
;         unsigned nloc = b.st[0], nx = b.st[1];
;         if (nloc == 0u) { xcd_barrier_complete(bar, b.x, nloc, nx); b.st[0] = nloc; b.st[1] = nx; }
;         const unsigned old = xb_add(&bar[XB_XSUB(b.x)], 1u);
;         const unsigned gen = old / nloc;
;         if (old + 1u == (gen + 1u) * nloc) {
;             __builtin_amdgcn_fence(__ATOMIC_RELEASE, "agent");
;             asm volatile("s_waitcnt vmcnt(0)" ::: "memory");
;             const unsigned og = xb_add(&bar[XB_TOP], 1u);
;             const unsigned tg = og / nx;
;             if (og + 1u == (tg + 1u) * nx) xb_add(&bar[XB_TOPGEN], 1u);
;             else XB_SPIN(xb_ld(&bar[XB_TOPGEN]) == tg, bar);
;             __builtin_amdgcn_fence(__ATOMIC_ACQUIRE, "agent");
;             asm volatile("s_waitcnt vmcnt(0)" ::: "memory");
;         } else {
;             XB_SPIN(xb_ld(&bar[XB_TOPGEN]) == gen, bar);
;             __builtin_amdgcn_fence(__ATOMIC_ACQUIRE, "agent");
;             asm volatile("s_waitcnt vmcnt(0)" ::: "memory");
;         }
;     }
;     __syncthreads();
.LBB0_70:
	s_waitcnt vmcnt(0) lgkmcnt(0)
	v_mov_b32_e32 v1, 0x27c20
	ds_read_b32 v2, v1
	ds_read_b32 v3, v1 offset:4
	buffer_inv sc1
	s_lshl_b32 s6, s33, 8
	s_add_u32 s6, s82, s6
	s_addc_u32 s7, s83, 0
	v_mov_b32_e32 v1, 0x1000
	v_mov_b32_e32 v4, 1
	global_atomic_add v5, v1, v4, s[6:7] offset:1024 sc0
	s_waitcnt vmcnt(0) lgkmcnt(0)
	v_add_u32_e32 v5, 1, v5
	v_cmp_eq_u32_e32 vcc, v5, v2
	s_and_saveexec_b64 s[6:7], vcc
	s_cbranch_execz .Lbar1_notlast
	buffer_wbl2 sc1
	s_waitcnt vmcnt(0)
	v_mov_b32_e32 v1, 0x7000
	global_atomic_add v1, v4, s[30:31] offset:1024
.Lbar1_notlast:
	s_or_b64 exec, exec, s[6:7]
	v_mov_b32_e32 v1, 0x7000
	s_mov_b32 s16, 0
.Lbar1_poll:
	global_load_dword v5, v1, s[30:31] offset:1024 sc1
	s_waitcnt vmcnt(0)
	v_cmp_ge_u32_e32 vcc, v5, v3
	s_cbranch_vccnz .Lbar1_go
	s_sleep 1
	s_add_u32 s16, s16, 1
	s_cmp_lt_u32 s16, 0x8000
	s_cbranch_scc1 .Lbar1_poll
.Lbar1_go:


;     __device__ __forceinline__ bool next(int i, Unit& u) const {
;         int L = i * G + c; if (L >= G1_ALL) return false;
;         u.nt = DM / 64; u.kind = 0;
;         if (L < G1_SPECIAL) { u.pm = MP / 256 + (L >> 3); u.pn = 30 + (L & 7); u.kind = 4; }
;         else if ((L -= G1_SPECIAL) < G1_PROMPT) { int pm, pn; pg8::tile_order(L, MP / 256, G1_NN, pm, pn); u.pm = pm; u.pn = pn; }
;         else if ((L -= G1_PROMPT) < G1_S2) { u.pm = MP / 256 + L / 30; u.pn = L % 30; }
;         else { const int r = L - G1_S2, t = r >> 4, pm = (r >> 2) & 3, pn = r & 3; u.pm = pm; u.pn = pn; u.kind = 1 + t;
;             if (t == 0) { u.A = HM + (size_t)pm * TSTEP4K; u.B = WKV + (size_t)pn * TSTEP4K; }
;             else if (t == 1) { u.A = HM + (size_t)pm * TSTEP4K; u.B = WKV + (size_t)(4 + pn) * TSTEP4K; }
;             else { u.A = WKV + (size_t)(4 + pm) * TSTEP4K; u.B = HM + (size_t)pn * TSTEP4K; }
;             return true; }
;         u.A = H + (size_t)u.pm * TSTEP4K; u.B = WIN + (size_t)u.pn * TSTEP4K;
;         return true;
; __global__ void __launch_bounds__(NTHR, 2) hybrid_fwd(Args args) {
;     ...
;     xcd_barrier(bar);
;     { Frame F = make_frame(lds);
;       Sched1 S{F.G, (int)blockIdx.x, (const char*)(F.ws + WS_H), (const char*)(F.ws + WS_HM), (const char*)(F.ws + WS_WIN), (const char*)(F.ws + WS_WKV)};
;       Epi1 E{WSP(bf16_t, WS_U), WSP(bf16_t, WS_SGA), WSP(bf16_t, WS_A), WSP(bf16_t, WS_SGB), WSP(bf16_t, WS_Q), WSP(bf16_t, WS_SGC), WSP(bf16_t, WS_KP), WSP(bf16_t, WS_VPT), F.out + O_MK, F.out + O_MV, (unsigned*)(F.ws + WS_CTL) + CW_QREADY};
;       pg8::gemm_phase<Epi1, Sched1, true, true>(F.lds, DM, DM, S, E); }
.LBB0_104:
	s_or_b64 exec, exec, s[4:5]
	s_waitcnt lgkmcnt(0)
	v_mov_b32_e32 v1, v0
	s_mov_b64 s[4:5], s[0:1]
	s_barrier
	s_load_dwordx4 s[8:11], s[4:5], 0xa8
	s_load_dwordx4 s[24:27], s[0:1], 0x70
	v_mov_b32_e32 v10, v0
	s_waitcnt lgkmcnt(0)
	s_add_u32 s29, s10, 0x1ba00000
	s_addc_u32 s74, s11, 0
	s_add_u32 s75, s10, 0x1b200000
	s_addc_u32 s76, s11, 0
	s_add_u32 s77, s10, 0x20e00000
	s_addc_u32 s78, s11, 0
	s_add_u32 s79, s10, 0x1fe00000
	s_addc_u32 s80, s11, 0
	s_cmpk_lt_i32 s2, 0xe0
	s_cselect_b64 s[6:7], -1, 0
	s_cmpk_gt_i32 s2, 0xdf
	v_readfirstlane_b32 s12, v10
	s_cbranch_scc1 .LBB0_111
	s_cmp_gt_i32 s2, 15
	s_cbranch_scc0 .LBB0_112
	s_cmpk_gt_u32 s2, 0x4cf
	s_cbranch_scc0 .LBB0_113
	s_cmpk_gt_u32 s2, 0x50b
	s_cbranch_scc0 .LBB0_114
	s_add_i32 s13, s2, 0xfffffaf4
	s_lshr_b32 s16, s13, 4
	s_bfe_u32 s4, s13, 0x20002
	s_and_b32 s62, s2, 3
	s_add_i32 s5, s16, 1
	s_cmp_gt_u32 s13, 15
	s_cbranch_scc0 .LBB0_115
	s_lshl_b32 s18, s4, 21
	s_cmp_lg_u32 s16, 1
	s_cbranch_scc0 .LBB0_116
	s_add_u32 s16, s79, s18
	s_addc_u32 s17, s80, 0
	s_add_u32 s66, s16, 0x800000
	s_addc_u32 s67, s17, 0
	s_lshl_b32 s16, s62, 21
	s_add_u32 s68, s75, s16
	s_addc_u32 s69, s76, 0
	s_mov_b64 s[16:17], 0
	s_branch .LBB0_117
